# J mainloop: LDS-DMA loads in saddr form (SGPR base + VGPR offset, +kstep via offset:128 with M0 compensated or a VCC-pair base); 16 VALU 64-bit address adds per iteration removed
# baseline (speedup 1.0000x reference)
; #define PG8_STAGE(bufoff, gbase, voff) do { _Pragma("unroll") for (int _i = 0; _i < 2; ++_i) \
;         __builtin_amdgcn_global_load_lds((const unsigned*)((const char*)(gbase) + (voff)[_i]), (LAS unsigned*)(lds + (bufoff) + ldsw + _i * 8192), 16, 0, 0); } while (0)
; #define PG8_LDA(dst, b, h) do { _Pragma("unroll") for (int m = 0; m < 4; ++m) _Pragma("unroll") for (int k = 0; k < 2; ++k) dst[m][k] = *(const LAS bf16x8*)(lds + PG8_SA(b, h) + aoff + m * 2048 + k * 1024); } while (0)
; #define PG8_LDB(dst, b, h) do { _Pragma("unroll") for (int n = 0; n < 2; ++n) _Pragma("unroll") for (int k = 0; k < 2; ++k) dst[n][k] = *(const LAS bf16x8*)(lds + PG8_SB(b, h) + boff + n * 2048 + k * 1024); } while (0)
; #define PG8_MMA(ai, bj, At, Bt) do { __builtin_amdgcn_s_setprio(1); _Pragma("unroll") for (int m = 0; m < 4; ++m) _Pragma("unroll") for (int n = 0; n < 2; ++n) _Pragma("unroll") for (int k = 0; k < 2; ++k) \
;         acc[ai][bj][m][n] = __builtin_amdgcn_mfma_f32_16x16x32_bf16(Bt[n][k], At[m][k], acc[ai][bj][m][n], 0, 0, 0); __builtin_amdgcn_s_setprio(0); } while (0)
; #define PG8_WAIT_V(n) asm volatile("s_waitcnt vmcnt(" #n ")" ::: "memory")
; #define PG8_WAIT_L(n) asm volatile("s_waitcnt lgkmcnt(" #n ")" ::: "memory")
; #define PG8_BAR __builtin_amdgcn_s_barrier()
; #define PG8_SCHED __builtin_amdgcn_sched_barrier(0)
; template <class Epi>
; __device__ __forceinline__ void gemm_phase(LAS unsigned char* lds, const Sched& S, const int K, const Epi& E) {
;     ...
;             const char* a1 = cA + (size_t)(t + 1) * kstep;
;             const char* a2 = last ? nA : cA + (size_t)(t + 2) * kstep; const char* b2 = last ? nB : cB + (size_t)(t + 2) * kstep;
;             const char* a3 = a2 + kstep; const char* b3 = b2 + kstep;
;             PG8_LDB(B0, 0, 0); PG8_LDB(B1, 0, 1); PG8_SCHED; PG8_LDA(At, 0, 0); PG8_STAGE(PG8_SA(1, 1), a1 + hstepA, voffA);
;             PG8_WAIT_V(8); PG8_WAIT_L(0); PG8_BAR; PG8_MMA(0, 0, At, B0); PG8_MMA(0, 1, At, B1); PG8_BAR; PG8_SCHED;
;             PG8_LDA(At, 0, 1); PG8_STAGE(PG8_SB(0, 0), b2, voffB); PG8_STAGE(PG8_SB(0, 1), b2 + hstepB, voffB); PG8_STAGE(PG8_SA(0, 0), a2, voffA);
;             PG8_WAIT_V(8); PG8_WAIT_L(0); PG8_BAR; PG8_MMA(1, 0, At, B0); PG8_MMA(1, 1, At, B1); PG8_BAR; PG8_SCHED;
.LBB0_1400:
	s_add_u32 s50, s36, 0xfff80080
	s_addc_u32 s51, s37, -1
	s_add_i32 s73, 0, 0x10000
	s_cmp_eq_u32 s72, 28
	s_cselect_b32 s53, s29, s51
	s_cselect_b32 s52, s28, s50
	s_cselect_b32 s51, s35, s71
	s_cselect_b32 s50, s34, s45
	s_add_i32 s78, 0, 0x14000
	v_add_u32_e32 v154, s73, v139
	v_add_u32_e32 v170, s78, v139
	ds_read_b128 v[142:145], v154
	ds_read_b128 v[146:149], v154 offset:1024
	ds_read_b128 v[150:153], v154 offset:2048
	ds_read_b128 v[154:157], v154 offset:3072
	ds_read_b128 v[158:161], v170
	ds_read_b128 v[162:165], v170 offset:1024
	ds_read_b128 v[166:169], v170 offset:2048
	ds_read_b128 v[198:201], v170 offset:3072
	s_add_i32 m0, s59, 0xc000
	ds_read_b128 v[202:205], v141
	ds_read_b128 v[206:209], v141 offset:1024
	ds_read_b128 v[210:213], v141 offset:2048
	ds_read_b128 v[214:217], v141 offset:3072
	ds_read_b128 v[218:221], v141 offset:4096
	ds_read_b128 v[228:231], v141 offset:5120
	ds_read_b128 v[232:235], v141 offset:6144
	ds_read_b128 v[236:239], v141 offset:7168
	global_load_lds_dwordx4 v134, s[36:37]
	s_add_i32 m0, s59, 0xe000
	s_nop 0
	global_load_lds_dwordx4 v136, s[36:37]
	s_waitcnt vmcnt(8)
	s_waitcnt lgkmcnt(0)
	s_barrier
	s_setprio 1
	s_waitcnt lgkmcnt(0)
	v_mfma_f32_16x16x32_bf16 v[124:127], v[142:145], v[202:205], v[124:127]
	v_mfma_f32_16x16x32_bf16 v[116:119], v[150:153], v[202:205], v[116:119]
	v_mfma_f32_16x16x32_bf16 v[108:111], v[142:145], v[210:213], v[108:111]
	v_mfma_f32_16x16x32_bf16 v[100:103], v[150:153], v[210:213], v[100:103]
	v_mfma_f32_16x16x32_bf16 v[92:95], v[142:145], v[218:221], v[92:95]
	v_mfma_f32_16x16x32_bf16 v[84:87], v[150:153], v[218:221], v[84:87]
	v_mfma_f32_16x16x32_bf16 v[76:79], v[142:145], v[232:235], v[76:79]
	v_mfma_f32_16x16x32_bf16 v[68:71], v[150:153], v[232:235], v[68:71]
	v_mfma_f32_16x16x32_bf16 v[124:127], v[146:149], v[206:209], v[124:127]
	v_mfma_f32_16x16x32_bf16 v[116:119], v[154:157], v[206:209], v[116:119]
	v_mfma_f32_16x16x32_bf16 v[108:111], v[146:149], v[214:217], v[108:111]
	v_mfma_f32_16x16x32_bf16 v[100:103], v[154:157], v[214:217], v[100:103]
	v_mfma_f32_16x16x32_bf16 v[92:95], v[146:149], v[228:231], v[92:95]
	v_mfma_f32_16x16x32_bf16 v[84:87], v[154:157], v[228:231], v[84:87]
	v_mfma_f32_16x16x32_bf16 v[76:79], v[146:149], v[236:239], v[76:79]
	v_mfma_f32_16x16x32_bf16 v[68:71], v[154:157], v[236:239], v[68:71]
	s_setprio 0
	s_setprio 1
	v_mfma_f32_16x16x32_bf16 v[120:123], v[158:161], v[202:205], v[120:123]
	v_mfma_f32_16x16x32_bf16 v[112:115], v[166:169], v[202:205], v[112:115]
	v_mfma_f32_16x16x32_bf16 v[104:107], v[158:161], v[210:213], v[104:107]
	v_mfma_f32_16x16x32_bf16 v[96:99], v[166:169], v[210:213], v[96:99]
	v_mfma_f32_16x16x32_bf16 v[88:91], v[158:161], v[218:221], v[88:91]
	v_mfma_f32_16x16x32_bf16 v[80:83], v[166:169], v[218:221], v[80:83]
	v_mfma_f32_16x16x32_bf16 v[72:75], v[158:161], v[232:235], v[72:75]
	v_mfma_f32_16x16x32_bf16 v[64:67], v[166:169], v[232:235], v[64:67]
	v_mfma_f32_16x16x32_bf16 v[120:123], v[162:165], v[206:209], v[120:123]
	v_mfma_f32_16x16x32_bf16 v[112:115], v[198:201], v[206:209], v[112:115]
	v_mfma_f32_16x16x32_bf16 v[104:107], v[162:165], v[214:217], v[104:107]
	v_mfma_f32_16x16x32_bf16 v[96:99], v[198:201], v[214:217], v[96:99]
	v_mfma_f32_16x16x32_bf16 v[88:91], v[162:165], v[228:231], v[88:91]
	v_mfma_f32_16x16x32_bf16 v[80:83], v[198:201], v[228:231], v[80:83]
	v_mfma_f32_16x16x32_bf16 v[72:75], v[162:165], v[236:239], v[72:75]
	v_mfma_f32_16x16x32_bf16 v[64:67], v[198:201], v[236:239], v[64:67]
	s_setprio 0
	s_barrier
	s_add_i32 s73, s73, s58
	s_mov_b32 m0, s73
	ds_read_b128 v[202:205], v141 offset:16384
	ds_read_b128 v[206:209], v141 offset:17408
	ds_read_b128 v[210:213], v141 offset:18432
	ds_read_b128 v[214:217], v141 offset:19456
	ds_read_b128 v[218:221], v141 offset:20480
	ds_read_b128 v[228:231], v141 offset:21504
	ds_read_b128 v[232:235], v141 offset:22528
	ds_read_b128 v[236:239], v141 offset:23552
	global_load_lds_dwordx4 v172, s[50:51]
	s_add_i32 m0, s73, 0x2000
	s_add_u32 s76, s50, 0x80000
	s_addc_u32 s77, s51, 0
	s_add_i32 s73, s78, s58
	global_load_lds_dwordx4 v128, s[50:51]
	s_mov_b32 m0, s73
	s_nop 0
	global_load_lds_dwordx4 v172, s[76:77]
	s_add_i32 m0, s73, 0x2000
	s_nop 0
	global_load_lds_dwordx4 v128, s[76:77]
	s_mov_b32 m0, s59
	s_nop 0
	global_load_lds_dwordx4 v132, s[52:53]
	s_mov_b32 m0, s60
	s_nop 0
	global_load_lds_dwordx4 v130, s[52:53]
	s_waitcnt vmcnt(8)
	s_waitcnt lgkmcnt(0)
	s_barrier
	s_setprio 1
	s_waitcnt lgkmcnt(0)
	v_mfma_f32_16x16x32_bf16 v[60:63], v[142:145], v[202:205], v[60:63]
	v_mfma_f32_16x16x32_bf16 v[52:55], v[150:153], v[202:205], v[52:55]
	v_mfma_f32_16x16x32_bf16 v[44:47], v[142:145], v[210:213], v[44:47]
	v_mfma_f32_16x16x32_bf16 v[36:39], v[150:153], v[210:213], v[36:39]
	v_mfma_f32_16x16x32_bf16 v[28:31], v[142:145], v[218:221], v[28:31]
	v_mfma_f32_16x16x32_bf16 v[20:23], v[150:153], v[218:221], v[20:23]
	v_mfma_f32_16x16x32_bf16 v[12:15], v[142:145], v[232:235], v[12:15]
	v_mfma_f32_16x16x32_bf16 v[4:7], v[150:153], v[232:235], v[4:7]
	v_mfma_f32_16x16x32_bf16 v[60:63], v[146:149], v[206:209], v[60:63]
	v_mfma_f32_16x16x32_bf16 v[52:55], v[154:157], v[206:209], v[52:55]
	v_mfma_f32_16x16x32_bf16 v[44:47], v[146:149], v[214:217], v[44:47]
	v_mfma_f32_16x16x32_bf16 v[36:39], v[154:157], v[214:217], v[36:39]
	v_mfma_f32_16x16x32_bf16 v[28:31], v[146:149], v[228:231], v[28:31]
	v_mfma_f32_16x16x32_bf16 v[20:23], v[154:157], v[228:231], v[20:23]
	v_mfma_f32_16x16x32_bf16 v[12:15], v[146:149], v[236:239], v[12:15]
	v_mfma_f32_16x16x32_bf16 v[4:7], v[154:157], v[236:239], v[4:7]
	s_setprio 0
	s_setprio 1
	v_mfma_f32_16x16x32_bf16 v[56:59], v[158:161], v[202:205], v[56:59]
	v_mfma_f32_16x16x32_bf16 v[48:51], v[166:169], v[202:205], v[48:51]
	v_mfma_f32_16x16x32_bf16 v[40:43], v[158:161], v[210:213], v[40:43]
	v_mfma_f32_16x16x32_bf16 v[32:35], v[166:169], v[210:213], v[32:35]
	v_mfma_f32_16x16x32_bf16 v[24:27], v[158:161], v[218:221], v[24:27]
	v_mfma_f32_16x16x32_bf16 v[16:19], v[166:169], v[218:221], v[16:19]
	v_mfma_f32_16x16x32_bf16 v[8:11], v[158:161], v[232:235], v[8:11]
	v_mfma_f32_16x16x32_bf16 v[0:3], v[166:169], v[232:235], v[0:3]
	v_mfma_f32_16x16x32_bf16 v[56:59], v[162:165], v[206:209], v[56:59]
	v_mfma_f32_16x16x32_bf16 v[48:51], v[198:201], v[206:209], v[48:51]
	v_mfma_f32_16x16x32_bf16 v[40:43], v[162:165], v[214:217], v[40:43]
	v_mfma_f32_16x16x32_bf16 v[32:35], v[198:201], v[214:217], v[32:35]
	v_mfma_f32_16x16x32_bf16 v[24:27], v[162:165], v[228:231], v[24:27]
	v_mfma_f32_16x16x32_bf16 v[16:19], v[198:201], v[228:231], v[16:19]
	v_mfma_f32_16x16x32_bf16 v[8:11], v[162:165], v[236:239], v[8:11]
	v_mfma_f32_16x16x32_bf16 v[0:3], v[198:201], v[236:239], v[0:3]
	s_setprio 0
	s_barrier
; #define PG8_STAGE(bufoff, gbase, voff) do { _Pragma("unroll") for (int _i = 0; _i < 2; ++_i) \
;         __builtin_amdgcn_global_load_lds((const unsigned*)((const char*)(gbase) + (voff)[_i]), (LAS unsigned*)(lds + (bufoff) + ldsw + _i * 8192), 16, 0, 0); } while (0)
; #define PG8_LDA(dst, b, h) do { _Pragma("unroll") for (int m = 0; m < 4; ++m) _Pragma("unroll") for (int k = 0; k < 2; ++k) dst[m][k] = *(const LAS bf16x8*)(lds + PG8_SA(b, h) + aoff + m * 2048 + k * 1024); } while (0)
; #define PG8_LDB(dst, b, h) do { _Pragma("unroll") for (int n = 0; n < 2; ++n) _Pragma("unroll") for (int k = 0; k < 2; ++k) dst[n][k] = *(const LAS bf16x8*)(lds + PG8_SB(b, h) + boff + n * 2048 + k * 1024); } while (0)
; #define PG8_MMA(ai, bj, At, Bt) do { __builtin_amdgcn_s_setprio(1); _Pragma("unroll") for (int m = 0; m < 4; ++m) _Pragma("unroll") for (int n = 0; n < 2; ++n) _Pragma("unroll") for (int k = 0; k < 2; ++k) \
;         acc[ai][bj][m][n] = __builtin_amdgcn_mfma_f32_16x16x32_bf16(Bt[n][k], At[m][k], acc[ai][bj][m][n], 0, 0, 0); __builtin_amdgcn_s_setprio(0); } while (0)
; #define PG8_WAIT_V(n) asm volatile("s_waitcnt vmcnt(" #n ")" ::: "memory")
; #define PG8_WAIT_L(n) asm volatile("s_waitcnt lgkmcnt(" #n ")" ::: "memory")
; #define PG8_BAR __builtin_amdgcn_s_barrier()
; #define PG8_SCHED __builtin_amdgcn_sched_barrier(0)
; template <class Epi>
; __device__ __forceinline__ void gemm_phase(LAS unsigned char* lds, const Sched& S, const int K, const Epi& E) {
;     ...
;             PG8_LDB(B0, 1, 0); PG8_LDB(B1, 1, 1); PG8_SCHED; PG8_LDA(At, 1, 0); PG8_STAGE(PG8_SA(0, 1), a2 + hstepA, voffA);
;             PG8_WAIT_V(8); PG8_WAIT_L(0); PG8_BAR; PG8_MMA(0, 0, At, B0); PG8_MMA(0, 1, At, B1); PG8_BAR; PG8_SCHED;
;             PG8_LDA(At, 1, 1); PG8_STAGE(PG8_SB(1, 0), b3, voffB); PG8_STAGE(PG8_SB(1, 1), b3 + hstepB, voffB); PG8_STAGE(PG8_SA(1, 0), a3, voffA);
;             PG8_WAIT_V(8); PG8_WAIT_L(0); PG8_BAR; PG8_MMA(1, 0, At, B0); PG8_MMA(1, 1, At, B1); PG8_BAR; PG8_SCHED;
	s_add_i32 s73, 0, 0x18000
	s_add_i32 s76, 0, 0x1c000
	v_add_u32_e32 v154, s73, v139
	v_add_u32_e32 v198, s76, v139
	ds_read_b128 v[142:145], v154
	ds_read_b128 v[146:149], v154 offset:1024
	ds_read_b128 v[150:153], v154 offset:2048
	ds_read_b128 v[154:157], v154 offset:3072
	ds_read_b128 v[158:161], v198
	ds_read_b128 v[162:165], v198 offset:1024
	ds_read_b128 v[166:169], v198 offset:2048
	ds_read_b128 v[198:201], v198 offset:3072
	s_add_u32 s52, s52, 0x80000
	s_addc_u32 s53, s53, 0
	s_mov_b32 m0, s63
	ds_read_b128 v[202:205], v141 offset:32768
	ds_read_b128 v[206:209], v141 offset:33792
	ds_read_b128 v[210:213], v141 offset:34816
	ds_read_b128 v[214:217], v141 offset:35840
	ds_read_b128 v[218:221], v141 offset:36864
	ds_read_b128 v[228:231], v141 offset:37888
	ds_read_b128 v[232:235], v141 offset:38912
	ds_read_b128 v[236:239], v141 offset:39936
	global_load_lds_dwordx4 v132, s[52:53]
	s_mov_b32 m0, s65
	s_nop 0
	global_load_lds_dwordx4 v130, s[52:53]
	s_waitcnt vmcnt(8)
	s_waitcnt lgkmcnt(0)
	s_barrier
	s_setprio 1
	s_waitcnt lgkmcnt(0)
	v_mfma_f32_16x16x32_bf16 v[124:127], v[142:145], v[202:205], v[124:127]
	v_mfma_f32_16x16x32_bf16 v[116:119], v[150:153], v[202:205], v[116:119]
	v_mfma_f32_16x16x32_bf16 v[108:111], v[142:145], v[210:213], v[108:111]
	v_mfma_f32_16x16x32_bf16 v[100:103], v[150:153], v[210:213], v[100:103]
	v_mfma_f32_16x16x32_bf16 v[92:95], v[142:145], v[218:221], v[92:95]
	v_mfma_f32_16x16x32_bf16 v[84:87], v[150:153], v[218:221], v[84:87]
	v_mfma_f32_16x16x32_bf16 v[76:79], v[142:145], v[232:235], v[76:79]
	v_mfma_f32_16x16x32_bf16 v[68:71], v[150:153], v[232:235], v[68:71]
	v_mfma_f32_16x16x32_bf16 v[124:127], v[146:149], v[206:209], v[124:127]
	v_mfma_f32_16x16x32_bf16 v[116:119], v[154:157], v[206:209], v[116:119]
	v_mfma_f32_16x16x32_bf16 v[108:111], v[146:149], v[214:217], v[108:111]
	v_mfma_f32_16x16x32_bf16 v[100:103], v[154:157], v[214:217], v[100:103]
	v_mfma_f32_16x16x32_bf16 v[92:95], v[146:149], v[228:231], v[92:95]
	v_mfma_f32_16x16x32_bf16 v[84:87], v[154:157], v[228:231], v[84:87]
	v_mfma_f32_16x16x32_bf16 v[76:79], v[146:149], v[236:239], v[76:79]
	v_mfma_f32_16x16x32_bf16 v[68:71], v[154:157], v[236:239], v[68:71]
	s_setprio 0
	s_setprio 1
	v_mfma_f32_16x16x32_bf16 v[120:123], v[158:161], v[202:205], v[120:123]
	v_mfma_f32_16x16x32_bf16 v[112:115], v[166:169], v[202:205], v[112:115]
	v_mfma_f32_16x16x32_bf16 v[104:107], v[158:161], v[210:213], v[104:107]
	v_mfma_f32_16x16x32_bf16 v[96:99], v[166:169], v[210:213], v[96:99]
	v_mfma_f32_16x16x32_bf16 v[88:91], v[158:161], v[218:221], v[88:91]
	v_mfma_f32_16x16x32_bf16 v[80:83], v[166:169], v[218:221], v[80:83]
	v_mfma_f32_16x16x32_bf16 v[72:75], v[158:161], v[232:235], v[72:75]
	v_mfma_f32_16x16x32_bf16 v[64:67], v[166:169], v[232:235], v[64:67]
	v_mfma_f32_16x16x32_bf16 v[120:123], v[162:165], v[206:209], v[120:123]
	v_mfma_f32_16x16x32_bf16 v[112:115], v[198:201], v[206:209], v[112:115]
	v_mfma_f32_16x16x32_bf16 v[104:107], v[162:165], v[214:217], v[104:107]
	v_mfma_f32_16x16x32_bf16 v[96:99], v[198:201], v[214:217], v[96:99]
	v_mfma_f32_16x16x32_bf16 v[88:91], v[162:165], v[228:231], v[88:91]
	v_mfma_f32_16x16x32_bf16 v[80:83], v[198:201], v[228:231], v[80:83]
	v_mfma_f32_16x16x32_bf16 v[72:75], v[162:165], v[236:239], v[72:75]
	v_mfma_f32_16x16x32_bf16 v[64:67], v[198:201], v[236:239], v[64:67]
	s_setprio 0
	s_barrier
	s_add_u32 vcc_lo, s52, 0xfff80080
	s_addc_u32 vcc_hi, s53, -1
	s_add_i32 s52, s73, s58
	s_add_i32 m0, s52, 0xffffff80
	ds_read_b128 v[202:205], v141 offset:49152
	ds_read_b128 v[206:209], v141 offset:50176
	ds_read_b128 v[210:213], v141 offset:51200
	ds_read_b128 v[214:217], v141 offset:52224
	ds_read_b128 v[218:221], v141 offset:53248
	ds_read_b128 v[228:231], v141 offset:54272
	ds_read_b128 v[232:235], v141 offset:55296
	ds_read_b128 v[236:239], v141 offset:56320
	global_load_lds_dwordx4 v172, s[50:51] offset:128
	s_add_i32 m0, s52, 0x1f80
	s_nop 0
	global_load_lds_dwordx4 v128, s[50:51] offset:128
	s_add_u32 s50, s50, 0x80080
	s_addc_u32 s51, s51, 0
	s_add_i32 s52, s76, s58
	s_mov_b32 m0, s52
	s_nop 0
	global_load_lds_dwordx4 v172, s[50:51]
	s_add_i32 m0, s52, 0x2000
	s_nop 0
	global_load_lds_dwordx4 v128, s[50:51]
	s_mov_b32 m0, s66
	s_nop 0
	global_load_lds_dwordx4 v132, vcc
	s_mov_b32 m0, s67
	s_nop 0
	global_load_lds_dwordx4 v130, vcc
	s_waitcnt vmcnt(8)
	s_waitcnt lgkmcnt(0)
	s_barrier
	s_setprio 1
	s_waitcnt lgkmcnt(0)
	v_mfma_f32_16x16x32_bf16 v[60:63], v[142:145], v[202:205], v[60:63]
	v_mfma_f32_16x16x32_bf16 v[52:55], v[150:153], v[202:205], v[52:55]
	v_mfma_f32_16x16x32_bf16 v[44:47], v[142:145], v[210:213], v[44:47]
	v_mfma_f32_16x16x32_bf16 v[36:39], v[150:153], v[210:213], v[36:39]
	v_mfma_f32_16x16x32_bf16 v[28:31], v[142:145], v[218:221], v[28:31]
	v_mfma_f32_16x16x32_bf16 v[20:23], v[150:153], v[218:221], v[20:23]
	v_mfma_f32_16x16x32_bf16 v[12:15], v[142:145], v[232:235], v[12:15]
	v_mfma_f32_16x16x32_bf16 v[4:7], v[150:153], v[232:235], v[4:7]
	v_mfma_f32_16x16x32_bf16 v[60:63], v[146:149], v[206:209], v[60:63]
	v_mfma_f32_16x16x32_bf16 v[52:55], v[154:157], v[206:209], v[52:55]
	v_mfma_f32_16x16x32_bf16 v[44:47], v[146:149], v[214:217], v[44:47]
	v_mfma_f32_16x16x32_bf16 v[36:39], v[154:157], v[214:217], v[36:39]
	v_mfma_f32_16x16x32_bf16 v[28:31], v[146:149], v[228:231], v[28:31]
	v_mfma_f32_16x16x32_bf16 v[20:23], v[154:157], v[228:231], v[20:23]
	v_mfma_f32_16x16x32_bf16 v[12:15], v[146:149], v[236:239], v[12:15]
	v_mfma_f32_16x16x32_bf16 v[4:7], v[154:157], v[236:239], v[4:7]
	s_setprio 0
	s_setprio 1
	v_mfma_f32_16x16x32_bf16 v[56:59], v[158:161], v[202:205], v[56:59]
	v_mfma_f32_16x16x32_bf16 v[48:51], v[166:169], v[202:205], v[48:51]
	v_mfma_f32_16x16x32_bf16 v[40:43], v[158:161], v[210:213], v[40:43]
	v_mfma_f32_16x16x32_bf16 v[32:35], v[166:169], v[210:213], v[32:35]
	v_mfma_f32_16x16x32_bf16 v[24:27], v[158:161], v[218:221], v[24:27]
	v_mfma_f32_16x16x32_bf16 v[16:19], v[166:169], v[218:221], v[16:19]
	v_mfma_f32_16x16x32_bf16 v[8:11], v[158:161], v[232:235], v[8:11]
	v_mfma_f32_16x16x32_bf16 v[0:3], v[166:169], v[232:235], v[0:3]
	v_mfma_f32_16x16x32_bf16 v[56:59], v[162:165], v[206:209], v[56:59]
	v_mfma_f32_16x16x32_bf16 v[48:51], v[198:201], v[206:209], v[48:51]
	v_mfma_f32_16x16x32_bf16 v[40:43], v[162:165], v[214:217], v[40:43]
	v_mfma_f32_16x16x32_bf16 v[32:35], v[198:201], v[214:217], v[32:35]
	v_mfma_f32_16x16x32_bf16 v[24:27], v[162:165], v[228:231], v[24:27]
	v_mfma_f32_16x16x32_bf16 v[16:19], v[198:201], v[228:231], v[16:19]
	v_mfma_f32_16x16x32_bf16 v[8:11], v[162:165], v[236:239], v[8:11]
	v_mfma_f32_16x16x32_bf16 v[0:3], v[198:201], v[236:239], v[0:3]
	s_setprio 0
	s_barrier
	s_add_i32 s72, s72, 2
	s_add_u32 s45, s45, 0x100
	s_addc_u32 s71, s71, 0
	s_add_u32 s36, s36, 0x100
	s_addc_u32 s37, s37, 0
	s_cmp_gt_u32 s72, 29
	s_cbranch_scc0 .LBB0_1400
	s_and_b64 vcc, exec, s[42:43]
	s_cbranch_vccz .LBB0_1403
	s_barrier
